# sample out-proj epilogue in the scan phase moved to the LDS-transposed coalesced layout
# speedup vs baseline: 1.0518x; 1.0012x over previous
; __device__ __forceinline__ unsigned pk(float lo, float hi) { return pg8::cvt_pk_bf16(lo, hi); }
; __device__ __forceinline__ float dot4(f32x4 v) { return (v[0] * v[0] + v[1] * v[1]) + (v[2] * v[2] + v[3] * v[3]); }
;     __device__ __forceinline__ void operator()(const pg8::f32x4 (&acc)[2][2][4][2], const pg8::Unit& u, int wr, int wc, int fr, int fq) const {
;         const int row0 = u.pm * 256 + wr * 64 + fr;
; #pragma unroll
;         for (int ai = 0; ai < 2; ++ai)
; #pragma unroll
;             for (int m = 0; m < 4; ++m) {
;                 const int row = row0 + ai * 128 + m * 16;
;                 const float* xi = (row < MP) ? xin_p + (size_t)row * DM : xin_s + (size_t)(row - MP) * DM;
;                 float sq = 0.f;
; #pragma unroll
;                 for (int bj = 0; bj < 2; ++bj) { const int col = u.pn * 256 + bj * 128 + wc * 32 + 8 * fq;
;                     const f32x4 a0 = *(const f32x4*)(xi + col) + acc[ai][bj][m][0], a1 = *(const f32x4*)(xi + col + 4) + acc[ai][bj][m][1];
;                     *(f32x4*)(xout + (size_t)row * DM + col) = a0; *(f32x4*)(xout + (size_t)row * DM + col + 4) = a1;
;                     u32x4 w; w.x = pk(a0[0], a0[1]); w.y = pk(a0[2], a0[3]); w.z = pk(a1[0], a1[1]); w.w = pk(a1[2], a1[3]);
;                     *(u32x4*)(xb + (size_t)row * DM + col) = w;
;                     sq += dot4(a0) + dot4(a1); }
;                 sq += __shfl_xor(sq, 16); sq += __shfl_xor(sq, 32);
;                 if (fq == 0) atomicAdd(ssout + row, sq);
;             }
; __global__ void __launch_bounds__(512, 2) fwd(Args a) {
;     ...
;             if (bx < 32) { pg8::Gemm g{(const bf16_t*)(ws + WS_OG), (const bf16_t*)(ws + WS_WGOUT), MT, DM, DM, 0}; SliceOrder S{64 + (bx >> 2), bx & 3};
;                 EpiResid E{a.in[I_XP], a.in[I_XS], (float*)(ws + WS_XR), XB, SS + 32768};
;                 pg8::gemm_phase<EpiResid, SliceOrder, true, true>(lds, g, S, E); }
.LBB0_597:
	s_add_u32 s8, s28, 0x5a00000
	s_addc_u32 s9, s29, 0
	s_add_u32 s6, s28, 0x30000
	s_addc_u32 s7, s29, 0
	v_lshl_or_b32 v251, v142, 3, s35
	s_cmp_lt_u32 s0, 64
	s_cselect_b32 s98, s12, s14
	s_cselect_b32 s99, s13, s15
	s_cselect_b32 s100, 0, 0x4000
	v_and_b32_e32 v196, 63, v0
	v_lshrrev_b32_e32 v197, 3, v196
	v_and_b32_e32 v194, 7, v196
	v_and_b32_e32 v142, -16, v143
	v_add_u32_e32 v142, v142, v197
	v_lshl_add_u32 v142, s0, 8, v142
	v_and_b32_e32 v250, -32, v251
	v_lshl_add_u32 v250, v194, 2, v250
	v_lshl_or_b32 v250, s3, 8, v250
	v_lshlrev_b32_e32 v182, 2, v142
	v_lshlrev_b32_e32 v195, 1, v250
	v_lshl_add_u32 v183, v142, 11, v195
	v_lshlrev_b32_e32 v195, 2, v250
	v_lshl_add_u32 v184, v142, 12, v195
	v_subrev_u32_e32 v190, s100, v142
	v_lshl_add_u32 v185, v190, 12, v195
	v_lshrrev_b32_e32 v190, 6, v0
	v_mul_u32_u24_e32 v190, 0x900, v190
	v_add_u32_e32 v190, 0x21000, v190
	v_mul_u32_u24_e32 v192, 0x90, v197
	v_lshl_add_u32 v192, v194, 4, v192
	v_add_u32_e32 v187, v190, v192
	v_and_b32_e32 v192, 15, v196
	v_mul_u32_u24_e32 v192, 0x90, v192
	v_lshrrev_b32_e32 v193, 4, v196
	v_lshl_add_u32 v192, v193, 5, v192
	v_add_u32_e32 v186, v190, v192
	v_add_u32_e32 v189, 0x8000, v185
	global_load_dwordx4 v[130:133], v185, s[98:99]
	global_load_dwordx4 v[134:137], v189, s[98:99]
	global_load_dwordx4 v[138:141], v185, s[98:99] offset:512
	global_load_dwordx4 v[144:147], v189, s[98:99] offset:512
	v_add_u32_e32 v188, 0x10000, v185
	v_add_u32_e32 v189, 0x8000, v188
	global_load_dwordx4 v[148:151], v188, s[98:99]
	global_load_dwordx4 v[152:155], v189, s[98:99]
	global_load_dwordx4 v[156:159], v188, s[98:99] offset:512
	global_load_dwordx4 v[160:163], v189, s[98:99] offset:512
	v_add_u32_e32 v188, 0x20000, v185
	v_add_u32_e32 v189, 0x8000, v188
	global_load_dwordx4 v[164:167], v188, s[98:99]
	global_load_dwordx4 v[170:173], v189, s[98:99]
	global_load_dwordx4 v[174:177], v188, s[98:99] offset:512
	global_load_dwordx4 v[178:181], v189, s[98:99] offset:512
	s_waitcnt vmcnt(8)
	v_add_u32_e32 v191, 0x8000, v184
	v_add_u32_e32 v193, 0x4000, v183
	ds_write_b128 v186, v[126:129]
	ds_write_b128 v186, v[122:125] offset:16
	ds_read_b128 v[126:129], v187
	ds_read_b128 v[122:125], v187 offset:1152
	s_waitcnt lgkmcnt(0)
	v_pk_add_f32 v[126:127], v[126:127], v[130:131]
	v_pk_add_f32 v[128:129], v[128:129], v[132:133]
	v_pk_add_f32 v[122:123], v[122:123], v[134:135]
	v_pk_add_f32 v[124:125], v[124:125], v[136:137]
	global_store_dwordx4 v184, v[126:129], s[8:9]
	global_store_dwordx4 v191, v[122:125], s[8:9]
	v_cvt_pk_bf16_f32 v246, v126, v127
	v_cvt_pk_bf16_f32 v247, v128, v129
	v_cvt_pk_bf16_f32 v248, v122, v123
	v_cvt_pk_bf16_f32 v249, v124, v125
	v_mul_f32_e32 v194, v126, v126
	v_mul_f32_e32 v195, v122, v122
	v_fmac_f32_e32 v194, v127, v127
	v_fmac_f32_e32 v195, v123, v123
	v_fmac_f32_e32 v194, v128, v128
	v_fmac_f32_e32 v195, v124, v124
	v_fmac_f32_e32 v194, v129, v129
	v_fmac_f32_e32 v195, v125, v125
	global_store_dwordx2 v183, v[246:247], s[64:65]
	global_store_dwordx2 v193, v[248:249], s[64:65]
	ds_write_b128 v186, v[118:121]
	ds_write_b128 v186, v[114:117] offset:16
	ds_read_b128 v[118:121], v187
	ds_read_b128 v[114:117], v187 offset:1152
	s_waitcnt lgkmcnt(0)
	v_pk_add_f32 v[118:119], v[118:119], v[138:139]
	v_pk_add_f32 v[120:121], v[120:121], v[140:141]
	v_pk_add_f32 v[114:115], v[114:115], v[144:145]
	v_pk_add_f32 v[116:117], v[116:117], v[146:147]
	global_store_dwordx4 v184, v[118:121], s[8:9] offset:512
	global_store_dwordx4 v191, v[114:117], s[8:9] offset:512
	v_cvt_pk_bf16_f32 v246, v118, v119
	v_cvt_pk_bf16_f32 v247, v120, v121
	v_cvt_pk_bf16_f32 v248, v114, v115
	v_cvt_pk_bf16_f32 v249, v116, v117
	v_fmac_f32_e32 v194, v118, v118
	v_fmac_f32_e32 v195, v114, v114
	v_fmac_f32_e32 v194, v119, v119
	v_fmac_f32_e32 v195, v115, v115
	v_fmac_f32_e32 v194, v120, v120
	v_fmac_f32_e32 v195, v116, v116
	v_fmac_f32_e32 v194, v121, v121
	v_fmac_f32_e32 v195, v117, v117
	global_store_dwordx2 v183, v[246:247], s[64:65] offset:256
	global_store_dwordx2 v193, v[248:249], s[64:65] offset:256
	s_nop 1
	v_add_f32_dpp v194, v194, v194 quad_perm:[1,0,3,2] row_mask:0xf bank_mask:0xf
	v_add_f32_dpp v195, v195, v195 quad_perm:[1,0,3,2] row_mask:0xf bank_mask:0xf
	s_nop 0
	v_add_f32_dpp v194, v194, v194 quad_perm:[2,3,0,1] row_mask:0xf bank_mask:0xf
	v_add_f32_dpp v195, v195, v195 quad_perm:[2,3,0,1] row_mask:0xf bank_mask:0xf
	s_nop 0
	v_add_f32_dpp v194, v194, v194 row_half_mirror row_mask:0xf bank_mask:0xf
	v_add_f32_dpp v195, v195, v195 row_half_mirror row_mask:0xf bank_mask:0xf
	s_nop 0
	s_mov_b32 exec_lo, 0x1010101
	s_mov_b32 exec_hi, 0x1010101
	global_atomic_add_f32 v182, v194, s[6:7]
	global_atomic_add_f32 v182, v195, s[6:7] offset:32
	s_mov_b64 exec, -1
	v_add_u32_e32 v188, 0x30000, v185
	v_add_u32_e32 v189, 0x8000, v188
	global_load_dwordx4 v[130:133], v188, s[98:99]
	global_load_dwordx4 v[134:137], v189, s[98:99]
	global_load_dwordx4 v[138:141], v188, s[98:99] offset:512
	global_load_dwordx4 v[144:147], v189, s[98:99] offset:512
	s_waitcnt vmcnt(18)
	v_add_u32_e32 v190, 0x10000, v184
	v_add_u32_e32 v192, 0x8000, v183
	v_add_u32_e32 v191, 0x8000, v190
	v_add_u32_e32 v193, 0x4000, v192
	ds_write_b128 v186, v[110:113]
	ds_write_b128 v186, v[106:109] offset:16
	ds_read_b128 v[110:113], v187
	ds_read_b128 v[106:109], v187 offset:1152
	s_waitcnt lgkmcnt(0)
; __device__ __forceinline__ unsigned pk(float lo, float hi) { return pg8::cvt_pk_bf16(lo, hi); }
; __device__ __forceinline__ float dot4(f32x4 v) { return (v[0] * v[0] + v[1] * v[1]) + (v[2] * v[2] + v[3] * v[3]); }
;     __device__ __forceinline__ void operator()(const pg8::f32x4 (&acc)[2][2][4][2], const pg8::Unit& u, int wr, int wc, int fr, int fq) const {
;     ...
;             for (int m = 0; m < 4; ++m) {
;                 const int row = row0 + ai * 128 + m * 16;
;                 const float* xi = (row < MP) ? xin_p + (size_t)row * DM : xin_s + (size_t)(row - MP) * DM;
;                 float sq = 0.f;
; #pragma unroll
;                 for (int bj = 0; bj < 2; ++bj) { const int col = u.pn * 256 + bj * 128 + wc * 32 + 8 * fq;
;                     const f32x4 a0 = *(const f32x4*)(xi + col) + acc[ai][bj][m][0], a1 = *(const f32x4*)(xi + col + 4) + acc[ai][bj][m][1];
;                     *(f32x4*)(xout + (size_t)row * DM + col) = a0; *(f32x4*)(xout + (size_t)row * DM + col + 4) = a1;
;                     u32x4 w; w.x = pk(a0[0], a0[1]); w.y = pk(a0[2], a0[3]); w.z = pk(a1[0], a1[1]); w.w = pk(a1[2], a1[3]);
;                     *(u32x4*)(xb + (size_t)row * DM + col) = w;
;                     sq += dot4(a0) + dot4(a1); }
;                 sq += __shfl_xor(sq, 16); sq += __shfl_xor(sq, 32);
;                 if (fq == 0) atomicAdd(ssout + row, sq);
;             }
	v_pk_add_f32 v[110:111], v[110:111], v[148:149]
	v_pk_add_f32 v[112:113], v[112:113], v[150:151]
	v_pk_add_f32 v[106:107], v[106:107], v[152:153]
	v_pk_add_f32 v[108:109], v[108:109], v[154:155]
	global_store_dwordx4 v190, v[110:113], s[8:9]
	global_store_dwordx4 v191, v[106:109], s[8:9]
	v_cvt_pk_bf16_f32 v246, v110, v111
	v_cvt_pk_bf16_f32 v247, v112, v113
	v_cvt_pk_bf16_f32 v248, v106, v107
	v_cvt_pk_bf16_f32 v249, v108, v109
	v_mul_f32_e32 v194, v110, v110
	v_mul_f32_e32 v195, v106, v106
	v_fmac_f32_e32 v194, v111, v111
	v_fmac_f32_e32 v195, v107, v107
	v_fmac_f32_e32 v194, v112, v112
	v_fmac_f32_e32 v195, v108, v108
	v_fmac_f32_e32 v194, v113, v113
	v_fmac_f32_e32 v195, v109, v109
	global_store_dwordx2 v192, v[246:247], s[64:65]
	global_store_dwordx2 v193, v[248:249], s[64:65]
	ds_write_b128 v186, v[102:105]
	ds_write_b128 v186, v[98:101] offset:16
	ds_read_b128 v[102:105], v187
	ds_read_b128 v[98:101], v187 offset:1152
	s_waitcnt lgkmcnt(0)
	v_pk_add_f32 v[102:103], v[102:103], v[156:157]
	v_pk_add_f32 v[104:105], v[104:105], v[158:159]
	v_pk_add_f32 v[98:99], v[98:99], v[160:161]
	v_pk_add_f32 v[100:101], v[100:101], v[162:163]
	global_store_dwordx4 v190, v[102:105], s[8:9] offset:512
	global_store_dwordx4 v191, v[98:101], s[8:9] offset:512
	v_cvt_pk_bf16_f32 v246, v102, v103
	v_cvt_pk_bf16_f32 v247, v104, v105
	v_cvt_pk_bf16_f32 v248, v98, v99
	v_cvt_pk_bf16_f32 v249, v100, v101
	v_fmac_f32_e32 v194, v102, v102
	v_fmac_f32_e32 v195, v98, v98
	v_fmac_f32_e32 v194, v103, v103
	v_fmac_f32_e32 v195, v99, v99
	v_fmac_f32_e32 v194, v104, v104
	v_fmac_f32_e32 v195, v100, v100
	v_fmac_f32_e32 v194, v105, v105
	v_fmac_f32_e32 v195, v101, v101
	global_store_dwordx2 v192, v[246:247], s[64:65] offset:256
	global_store_dwordx2 v193, v[248:249], s[64:65] offset:256
	s_nop 1
	v_add_f32_dpp v194, v194, v194 quad_perm:[1,0,3,2] row_mask:0xf bank_mask:0xf
	v_add_f32_dpp v195, v195, v195 quad_perm:[1,0,3,2] row_mask:0xf bank_mask:0xf
	s_nop 0
	v_add_f32_dpp v194, v194, v194 quad_perm:[2,3,0,1] row_mask:0xf bank_mask:0xf
	v_add_f32_dpp v195, v195, v195 quad_perm:[2,3,0,1] row_mask:0xf bank_mask:0xf
	s_nop 0
	v_add_f32_dpp v194, v194, v194 row_half_mirror row_mask:0xf bank_mask:0xf
	v_add_f32_dpp v195, v195, v195 row_half_mirror row_mask:0xf bank_mask:0xf
	s_nop 0
	s_mov_b32 exec_lo, 0x1010101
	s_mov_b32 exec_hi, 0x1010101
	global_atomic_add_f32 v182, v194, s[6:7] offset:64
	global_atomic_add_f32 v182, v195, s[6:7] offset:96
	s_mov_b64 exec, -1
	v_add_u32_e32 v188, 0x80000, v185
	v_add_u32_e32 v189, 0x8000, v188
	global_load_dwordx4 v[148:151], v188, s[98:99]
	global_load_dwordx4 v[152:155], v189, s[98:99]
	global_load_dwordx4 v[156:159], v188, s[98:99] offset:512
	global_load_dwordx4 v[160:163], v189, s[98:99] offset:512
	s_waitcnt vmcnt(28)
	v_add_u32_e32 v190, 0x20000, v184
	v_add_u32_e32 v192, 0x10000, v183
	v_add_u32_e32 v191, 0x8000, v190
	v_add_u32_e32 v193, 0x4000, v192
	ds_write_b128 v186, v[94:97]
	ds_write_b128 v186, v[90:93] offset:16
	ds_read_b128 v[94:97], v187
	ds_read_b128 v[90:93], v187 offset:1152
	s_waitcnt lgkmcnt(0)
	v_pk_add_f32 v[94:95], v[94:95], v[164:165]
	v_pk_add_f32 v[96:97], v[96:97], v[166:167]
	v_pk_add_f32 v[90:91], v[90:91], v[170:171]
	v_pk_add_f32 v[92:93], v[92:93], v[172:173]
	global_store_dwordx4 v190, v[94:97], s[8:9]
	global_store_dwordx4 v191, v[90:93], s[8:9]
	v_cvt_pk_bf16_f32 v246, v94, v95
	v_cvt_pk_bf16_f32 v247, v96, v97
	v_cvt_pk_bf16_f32 v248, v90, v91
	v_cvt_pk_bf16_f32 v249, v92, v93
	v_mul_f32_e32 v194, v94, v94
	v_mul_f32_e32 v195, v90, v90
	v_fmac_f32_e32 v194, v95, v95
	v_fmac_f32_e32 v195, v91, v91
	v_fmac_f32_e32 v194, v96, v96
	v_fmac_f32_e32 v195, v92, v92
	v_fmac_f32_e32 v194, v97, v97
	v_fmac_f32_e32 v195, v93, v93
	global_store_dwordx2 v192, v[246:247], s[64:65]
	global_store_dwordx2 v193, v[248:249], s[64:65]
	ds_write_b128 v186, v[86:89]
	ds_write_b128 v186, v[82:85] offset:16
	ds_read_b128 v[86:89], v187
	ds_read_b128 v[82:85], v187 offset:1152
	s_waitcnt lgkmcnt(0)
	v_pk_add_f32 v[86:87], v[86:87], v[174:175]
	v_pk_add_f32 v[88:89], v[88:89], v[176:177]
	v_pk_add_f32 v[82:83], v[82:83], v[178:179]
	v_pk_add_f32 v[84:85], v[84:85], v[180:181]
	global_store_dwordx4 v190, v[86:89], s[8:9] offset:512
	global_store_dwordx4 v191, v[82:85], s[8:9] offset:512
	v_cvt_pk_bf16_f32 v246, v86, v87
	v_cvt_pk_bf16_f32 v247, v88, v89
	v_cvt_pk_bf16_f32 v248, v82, v83
	v_cvt_pk_bf16_f32 v249, v84, v85
	v_fmac_f32_e32 v194, v86, v86
	v_fmac_f32_e32 v195, v82, v82
	v_fmac_f32_e32 v194, v87, v87
	v_fmac_f32_e32 v195, v83, v83
	v_fmac_f32_e32 v194, v88, v88
	v_fmac_f32_e32 v195, v84, v84
	v_fmac_f32_e32 v194, v89, v89
	v_fmac_f32_e32 v195, v85, v85
	global_store_dwordx2 v192, v[246:247], s[64:65] offset:256
	global_store_dwordx2 v193, v[248:249], s[64:65] offset:256
	s_nop 1
	v_add_f32_dpp v194, v194, v194 quad_perm:[1,0,3,2] row_mask:0xf bank_mask:0xf
	v_add_f32_dpp v195, v195, v195 quad_perm:[1,0,3,2] row_mask:0xf bank_mask:0xf
	s_nop 0
	v_add_f32_dpp v194, v194, v194 quad_perm:[2,3,0,1] row_mask:0xf bank_mask:0xf
	v_add_f32_dpp v195, v195, v195 quad_perm:[2,3,0,1] row_mask:0xf bank_mask:0xf
	s_nop 0
	v_add_f32_dpp v194, v194, v194 row_half_mirror row_mask:0xf bank_mask:0xf
	v_add_f32_dpp v195, v195, v195 row_half_mirror row_mask:0xf bank_mask:0xf
	s_nop 0
	s_mov_b32 exec_lo, 0x1010101
	s_mov_b32 exec_hi, 0x1010101
	global_atomic_add_f32 v182, v194, s[6:7] offset:128
	global_atomic_add_f32 v182, v195, s[6:7] offset:160
	s_mov_b64 exec, -1
	v_add_u32_e32 v188, 0x90000, v185
	v_add_u32_e32 v189, 0x8000, v188
	global_load_dwordx4 v[164:167], v188, s[98:99]
	global_load_dwordx4 v[170:173], v189, s[98:99]
	global_load_dwordx4 v[174:177], v188, s[98:99] offset:512
	global_load_dwordx4 v[178:181], v189, s[98:99] offset:512
	s_waitcnt vmcnt(28)
; __device__ __forceinline__ unsigned pk(float lo, float hi) { return pg8::cvt_pk_bf16(lo, hi); }
; __device__ __forceinline__ float dot4(f32x4 v) { return (v[0] * v[0] + v[1] * v[1]) + (v[2] * v[2] + v[3] * v[3]); }
;     __device__ __forceinline__ void operator()(const pg8::f32x4 (&acc)[2][2][4][2], const pg8::Unit& u, int wr, int wc, int fr, int fq) const {
;     ...
;             for (int m = 0; m < 4; ++m) {
;                 const int row = row0 + ai * 128 + m * 16;
;                 const float* xi = (row < MP) ? xin_p + (size_t)row * DM : xin_s + (size_t)(row - MP) * DM;
;                 float sq = 0.f;
; #pragma unroll
;                 for (int bj = 0; bj < 2; ++bj) { const int col = u.pn * 256 + bj * 128 + wc * 32 + 8 * fq;
;                     const f32x4 a0 = *(const f32x4*)(xi + col) + acc[ai][bj][m][0], a1 = *(const f32x4*)(xi + col + 4) + acc[ai][bj][m][1];
;                     *(f32x4*)(xout + (size_t)row * DM + col) = a0; *(f32x4*)(xout + (size_t)row * DM + col + 4) = a1;
;                     u32x4 w; w.x = pk(a0[0], a0[1]); w.y = pk(a0[2], a0[3]); w.z = pk(a1[0], a1[1]); w.w = pk(a1[2], a1[3]);
;                     *(u32x4*)(xb + (size_t)row * DM + col) = w;
;                     sq += dot4(a0) + dot4(a1); }
;                 sq += __shfl_xor(sq, 16); sq += __shfl_xor(sq, 32);
;                 if (fq == 0) atomicAdd(ssout + row, sq);
;             }
	v_add_u32_e32 v190, 0x30000, v184
	v_add_u32_e32 v192, 0x18000, v183
	v_add_u32_e32 v191, 0x8000, v190
	v_add_u32_e32 v193, 0x4000, v192
	ds_write_b128 v186, v[78:81]
	ds_write_b128 v186, v[74:77] offset:16
	ds_read_b128 v[78:81], v187
	ds_read_b128 v[74:77], v187 offset:1152
	s_waitcnt lgkmcnt(0)
	v_pk_add_f32 v[78:79], v[78:79], v[130:131]
	v_pk_add_f32 v[80:81], v[80:81], v[132:133]
	v_pk_add_f32 v[74:75], v[74:75], v[134:135]
	v_pk_add_f32 v[76:77], v[76:77], v[136:137]
	global_store_dwordx4 v190, v[78:81], s[8:9]
	global_store_dwordx4 v191, v[74:77], s[8:9]
	v_cvt_pk_bf16_f32 v246, v78, v79
	v_cvt_pk_bf16_f32 v247, v80, v81
	v_cvt_pk_bf16_f32 v248, v74, v75
	v_cvt_pk_bf16_f32 v249, v76, v77
	v_mul_f32_e32 v194, v78, v78
	v_mul_f32_e32 v195, v74, v74
	v_fmac_f32_e32 v194, v79, v79
	v_fmac_f32_e32 v195, v75, v75
	v_fmac_f32_e32 v194, v80, v80
	v_fmac_f32_e32 v195, v76, v76
	v_fmac_f32_e32 v194, v81, v81
	v_fmac_f32_e32 v195, v77, v77
	global_store_dwordx2 v192, v[246:247], s[64:65]
	global_store_dwordx2 v193, v[248:249], s[64:65]
	ds_write_b128 v186, v[70:73]
	ds_write_b128 v186, v[66:69] offset:16
	ds_read_b128 v[70:73], v187
	ds_read_b128 v[66:69], v187 offset:1152
	s_waitcnt lgkmcnt(0)
	v_pk_add_f32 v[70:71], v[70:71], v[138:139]
	v_pk_add_f32 v[72:73], v[72:73], v[140:141]
	v_pk_add_f32 v[66:67], v[66:67], v[144:145]
	v_pk_add_f32 v[68:69], v[68:69], v[146:147]
	global_store_dwordx4 v190, v[70:73], s[8:9] offset:512
	global_store_dwordx4 v191, v[66:69], s[8:9] offset:512
	v_cvt_pk_bf16_f32 v246, v70, v71
	v_cvt_pk_bf16_f32 v247, v72, v73
	v_cvt_pk_bf16_f32 v248, v66, v67
	v_cvt_pk_bf16_f32 v249, v68, v69
	v_fmac_f32_e32 v194, v70, v70
	v_fmac_f32_e32 v195, v66, v66
	v_fmac_f32_e32 v194, v71, v71
	v_fmac_f32_e32 v195, v67, v67
	v_fmac_f32_e32 v194, v72, v72
	v_fmac_f32_e32 v195, v68, v68
	v_fmac_f32_e32 v194, v73, v73
	v_fmac_f32_e32 v195, v69, v69
	global_store_dwordx2 v192, v[246:247], s[64:65] offset:256
	global_store_dwordx2 v193, v[248:249], s[64:65] offset:256
	s_nop 1
	v_add_f32_dpp v194, v194, v194 quad_perm:[1,0,3,2] row_mask:0xf bank_mask:0xf
	v_add_f32_dpp v195, v195, v195 quad_perm:[1,0,3,2] row_mask:0xf bank_mask:0xf
	s_nop 0
	v_add_f32_dpp v194, v194, v194 quad_perm:[2,3,0,1] row_mask:0xf bank_mask:0xf
	v_add_f32_dpp v195, v195, v195 quad_perm:[2,3,0,1] row_mask:0xf bank_mask:0xf
	s_nop 0
	v_add_f32_dpp v194, v194, v194 row_half_mirror row_mask:0xf bank_mask:0xf
	v_add_f32_dpp v195, v195, v195 row_half_mirror row_mask:0xf bank_mask:0xf
	s_nop 0
	s_mov_b32 exec_lo, 0x1010101
	s_mov_b32 exec_hi, 0x1010101
	global_atomic_add_f32 v182, v194, s[6:7] offset:192
	global_atomic_add_f32 v182, v195, s[6:7] offset:224
	s_mov_b64 exec, -1
	v_add_u32_e32 v188, 0xa0000, v185
	v_add_u32_e32 v189, 0x8000, v188
	global_load_dwordx4 v[130:133], v188, s[98:99]
	global_load_dwordx4 v[134:137], v189, s[98:99]
	global_load_dwordx4 v[138:141], v188, s[98:99] offset:512
	global_load_dwordx4 v[144:147], v189, s[98:99] offset:512
	s_waitcnt vmcnt(28)
	v_add_u32_e32 v190, 0x80000, v184
	v_add_u32_e32 v192, 0x40000, v183
	v_add_u32_e32 v191, 0x8000, v190
	v_add_u32_e32 v193, 0x4000, v192
	ds_write_b128 v186, v[62:65]
	ds_write_b128 v186, v[58:61] offset:16
	ds_read_b128 v[62:65], v187
	ds_read_b128 v[58:61], v187 offset:1152
	s_waitcnt lgkmcnt(0)
	v_pk_add_f32 v[62:63], v[62:63], v[148:149]
	v_pk_add_f32 v[64:65], v[64:65], v[150:151]
	v_pk_add_f32 v[58:59], v[58:59], v[152:153]
	v_pk_add_f32 v[60:61], v[60:61], v[154:155]
	global_store_dwordx4 v190, v[62:65], s[8:9]
	global_store_dwordx4 v191, v[58:61], s[8:9]
	v_cvt_pk_bf16_f32 v246, v62, v63
	v_cvt_pk_bf16_f32 v247, v64, v65
	v_cvt_pk_bf16_f32 v248, v58, v59
	v_cvt_pk_bf16_f32 v249, v60, v61
	v_mul_f32_e32 v194, v62, v62
	v_mul_f32_e32 v195, v58, v58
	v_fmac_f32_e32 v194, v63, v63
	v_fmac_f32_e32 v195, v59, v59
	v_fmac_f32_e32 v194, v64, v64
	v_fmac_f32_e32 v195, v60, v60
	v_fmac_f32_e32 v194, v65, v65
	v_fmac_f32_e32 v195, v61, v61
	global_store_dwordx2 v192, v[246:247], s[64:65]
	global_store_dwordx2 v193, v[248:249], s[64:65]
	ds_write_b128 v186, v[54:57]
	ds_write_b128 v186, v[50:53] offset:16
	ds_read_b128 v[54:57], v187
	ds_read_b128 v[50:53], v187 offset:1152
	s_waitcnt lgkmcnt(0)
	v_pk_add_f32 v[54:55], v[54:55], v[156:157]
	v_pk_add_f32 v[56:57], v[56:57], v[158:159]
	v_pk_add_f32 v[50:51], v[50:51], v[160:161]
	v_pk_add_f32 v[52:53], v[52:53], v[162:163]
	global_store_dwordx4 v190, v[54:57], s[8:9] offset:512
	global_store_dwordx4 v191, v[50:53], s[8:9] offset:512
	v_cvt_pk_bf16_f32 v246, v54, v55
	v_cvt_pk_bf16_f32 v247, v56, v57
	v_cvt_pk_bf16_f32 v248, v50, v51
	v_cvt_pk_bf16_f32 v249, v52, v53
	v_fmac_f32_e32 v194, v54, v54
	v_fmac_f32_e32 v195, v50, v50
	v_fmac_f32_e32 v194, v55, v55
	v_fmac_f32_e32 v195, v51, v51
	v_fmac_f32_e32 v194, v56, v56
	v_fmac_f32_e32 v195, v52, v52
	v_fmac_f32_e32 v194, v57, v57
	v_fmac_f32_e32 v195, v53, v53
	global_store_dwordx2 v192, v[246:247], s[64:65] offset:256
	global_store_dwordx2 v193, v[248:249], s[64:65] offset:256
	s_nop 1
	v_add_f32_dpp v194, v194, v194 quad_perm:[1,0,3,2] row_mask:0xf bank_mask:0xf
	v_add_f32_dpp v195, v195, v195 quad_perm:[1,0,3,2] row_mask:0xf bank_mask:0xf
	s_nop 0
	v_add_f32_dpp v194, v194, v194 quad_perm:[2,3,0,1] row_mask:0xf bank_mask:0xf
	v_add_f32_dpp v195, v195, v195 quad_perm:[2,3,0,1] row_mask:0xf bank_mask:0xf
	s_nop 0
	v_add_f32_dpp v194, v194, v194 row_half_mirror row_mask:0xf bank_mask:0xf
	v_add_f32_dpp v195, v195, v195 row_half_mirror row_mask:0xf bank_mask:0xf
	s_nop 0
	s_mov_b32 exec_lo, 0x1010101
	s_mov_b32 exec_hi, 0x1010101
	global_atomic_add_f32 v182, v194, s[6:7] offset:512
	global_atomic_add_f32 v182, v195, s[6:7] offset:544
	s_mov_b64 exec, -1
	v_add_u32_e32 v188, 0xb0000, v185
	v_add_u32_e32 v189, 0x8000, v188
	global_load_dwordx4 v[148:151], v188, s[98:99]
	global_load_dwordx4 v[152:155], v189, s[98:99]
	global_load_dwordx4 v[156:159], v188, s[98:99] offset:512
	global_load_dwordx4 v[160:163], v189, s[98:99] offset:512
	s_waitcnt vmcnt(28)
; __device__ __forceinline__ unsigned pk(float lo, float hi) { return pg8::cvt_pk_bf16(lo, hi); }
; __device__ __forceinline__ float dot4(f32x4 v) { return (v[0] * v[0] + v[1] * v[1]) + (v[2] * v[2] + v[3] * v[3]); }
;     __device__ __forceinline__ void operator()(const pg8::f32x4 (&acc)[2][2][4][2], const pg8::Unit& u, int wr, int wc, int fr, int fq) const {
;     ...
;             for (int m = 0; m < 4; ++m) {
;                 const int row = row0 + ai * 128 + m * 16;
;                 const float* xi = (row < MP) ? xin_p + (size_t)row * DM : xin_s + (size_t)(row - MP) * DM;
;                 float sq = 0.f;
; #pragma unroll
;                 for (int bj = 0; bj < 2; ++bj) { const int col = u.pn * 256 + bj * 128 + wc * 32 + 8 * fq;
;                     const f32x4 a0 = *(const f32x4*)(xi + col) + acc[ai][bj][m][0], a1 = *(const f32x4*)(xi + col + 4) + acc[ai][bj][m][1];
;                     *(f32x4*)(xout + (size_t)row * DM + col) = a0; *(f32x4*)(xout + (size_t)row * DM + col + 4) = a1;
;                     u32x4 w; w.x = pk(a0[0], a0[1]); w.y = pk(a0[2], a0[3]); w.z = pk(a1[0], a1[1]); w.w = pk(a1[2], a1[3]);
;                     *(u32x4*)(xb + (size_t)row * DM + col) = w;
;                     sq += dot4(a0) + dot4(a1); }
;                 sq += __shfl_xor(sq, 16); sq += __shfl_xor(sq, 32);
;                 if (fq == 0) atomicAdd(ssout + row, sq);
;             }
	v_add_u32_e32 v190, 0x90000, v184
	v_add_u32_e32 v192, 0x48000, v183
	v_add_u32_e32 v191, 0x8000, v190
	v_add_u32_e32 v193, 0x4000, v192
	ds_write_b128 v186, v[46:49]
	ds_write_b128 v186, v[42:45] offset:16
	ds_read_b128 v[46:49], v187
	ds_read_b128 v[42:45], v187 offset:1152
	s_waitcnt lgkmcnt(0)
	v_pk_add_f32 v[46:47], v[46:47], v[164:165]
	v_pk_add_f32 v[48:49], v[48:49], v[166:167]
	v_pk_add_f32 v[42:43], v[42:43], v[170:171]
	v_pk_add_f32 v[44:45], v[44:45], v[172:173]
	global_store_dwordx4 v190, v[46:49], s[8:9]
	global_store_dwordx4 v191, v[42:45], s[8:9]
	v_cvt_pk_bf16_f32 v246, v46, v47
	v_cvt_pk_bf16_f32 v247, v48, v49
	v_cvt_pk_bf16_f32 v248, v42, v43
	v_cvt_pk_bf16_f32 v249, v44, v45
	v_mul_f32_e32 v194, v46, v46
	v_mul_f32_e32 v195, v42, v42
	v_fmac_f32_e32 v194, v47, v47
	v_fmac_f32_e32 v195, v43, v43
	v_fmac_f32_e32 v194, v48, v48
	v_fmac_f32_e32 v195, v44, v44
	v_fmac_f32_e32 v194, v49, v49
	v_fmac_f32_e32 v195, v45, v45
	global_store_dwordx2 v192, v[246:247], s[64:65]
	global_store_dwordx2 v193, v[248:249], s[64:65]
	ds_write_b128 v186, v[38:41]
	ds_write_b128 v186, v[34:37] offset:16
	ds_read_b128 v[38:41], v187
	ds_read_b128 v[34:37], v187 offset:1152
	s_waitcnt lgkmcnt(0)
	v_pk_add_f32 v[38:39], v[38:39], v[174:175]
	v_pk_add_f32 v[40:41], v[40:41], v[176:177]
	v_pk_add_f32 v[34:35], v[34:35], v[178:179]
	v_pk_add_f32 v[36:37], v[36:37], v[180:181]
	global_store_dwordx4 v190, v[38:41], s[8:9] offset:512
	global_store_dwordx4 v191, v[34:37], s[8:9] offset:512
	v_cvt_pk_bf16_f32 v246, v38, v39
	v_cvt_pk_bf16_f32 v247, v40, v41
	v_cvt_pk_bf16_f32 v248, v34, v35
	v_cvt_pk_bf16_f32 v249, v36, v37
	v_fmac_f32_e32 v194, v38, v38
	v_fmac_f32_e32 v195, v34, v34
	v_fmac_f32_e32 v194, v39, v39
	v_fmac_f32_e32 v195, v35, v35
	v_fmac_f32_e32 v194, v40, v40
	v_fmac_f32_e32 v195, v36, v36
	v_fmac_f32_e32 v194, v41, v41
	v_fmac_f32_e32 v195, v37, v37
	global_store_dwordx2 v192, v[246:247], s[64:65] offset:256
	global_store_dwordx2 v193, v[248:249], s[64:65] offset:256
	s_nop 1
	v_add_f32_dpp v194, v194, v194 quad_perm:[1,0,3,2] row_mask:0xf bank_mask:0xf
	v_add_f32_dpp v195, v195, v195 quad_perm:[1,0,3,2] row_mask:0xf bank_mask:0xf
	s_nop 0
	v_add_f32_dpp v194, v194, v194 quad_perm:[2,3,0,1] row_mask:0xf bank_mask:0xf
	v_add_f32_dpp v195, v195, v195 quad_perm:[2,3,0,1] row_mask:0xf bank_mask:0xf
	s_nop 0
	v_add_f32_dpp v194, v194, v194 row_half_mirror row_mask:0xf bank_mask:0xf
	v_add_f32_dpp v195, v195, v195 row_half_mirror row_mask:0xf bank_mask:0xf
	s_nop 0
	s_mov_b32 exec_lo, 0x1010101
	s_mov_b32 exec_hi, 0x1010101
	global_atomic_add_f32 v182, v194, s[6:7] offset:576
	global_atomic_add_f32 v182, v195, s[6:7] offset:608
	s_mov_b64 exec, -1
	s_waitcnt vmcnt(24)
	v_add_u32_e32 v190, 0xa0000, v184
	v_add_u32_e32 v192, 0x50000, v183
	v_add_u32_e32 v191, 0x8000, v190
	v_add_u32_e32 v193, 0x4000, v192
	ds_write_b128 v186, v[30:33]
	ds_write_b128 v186, v[26:29] offset:16
	ds_read_b128 v[30:33], v187
	ds_read_b128 v[26:29], v187 offset:1152
	s_waitcnt lgkmcnt(0)
	v_pk_add_f32 v[30:31], v[30:31], v[130:131]
	v_pk_add_f32 v[32:33], v[32:33], v[132:133]
	v_pk_add_f32 v[26:27], v[26:27], v[134:135]
	v_pk_add_f32 v[28:29], v[28:29], v[136:137]
	global_store_dwordx4 v190, v[30:33], s[8:9]
	global_store_dwordx4 v191, v[26:29], s[8:9]
	v_cvt_pk_bf16_f32 v246, v30, v31
	v_cvt_pk_bf16_f32 v247, v32, v33
	v_cvt_pk_bf16_f32 v248, v26, v27
	v_cvt_pk_bf16_f32 v249, v28, v29
	v_mul_f32_e32 v194, v30, v30
	v_mul_f32_e32 v195, v26, v26
	v_fmac_f32_e32 v194, v31, v31
	v_fmac_f32_e32 v195, v27, v27
	v_fmac_f32_e32 v194, v32, v32
	v_fmac_f32_e32 v195, v28, v28
	v_fmac_f32_e32 v194, v33, v33
	v_fmac_f32_e32 v195, v29, v29
	global_store_dwordx2 v192, v[246:247], s[64:65]
	global_store_dwordx2 v193, v[248:249], s[64:65]
	ds_write_b128 v186, v[22:25]
	ds_write_b128 v186, v[18:21] offset:16
	ds_read_b128 v[22:25], v187
	ds_read_b128 v[18:21], v187 offset:1152
	s_waitcnt lgkmcnt(0)
; #define PG8_WAIT_V(n) asm volatile("s_waitcnt vmcnt(" #n ")" ::: "memory")
; #define PG8_BAR __builtin_amdgcn_s_barrier()
; __device__ __forceinline__ unsigned pk(float lo, float hi) { return pg8::cvt_pk_bf16(lo, hi); }
; __device__ __forceinline__ float dot4(f32x4 v) { return (v[0] * v[0] + v[1] * v[1]) + (v[2] * v[2] + v[3] * v[3]); }
; template <class Epi, class Sched, bool ALIGN_EPI = false, bool SP2 = false>
; __device__ __forceinline__ void gemm_phase(PG8_LAS unsigned char* lds, const Gemm g, const Sched& S, const Epi& E) {
;     ...
;     PG8_WAIT_V(0);
;     if constexpr (!ALIGN_EPI) { if (wr == 0) PG8_BAR; }
;     PG8_BAR;
;     __device__ __forceinline__ void operator()(const pg8::f32x4 (&acc)[2][2][4][2], const pg8::Unit& u, int wr, int wc, int fr, int fq) const {
;     ...
;             for (int m = 0; m < 4; ++m) {
;                 const int row = row0 + ai * 128 + m * 16;
;                 const float* xi = (row < MP) ? xin_p + (size_t)row * DM : xin_s + (size_t)(row - MP) * DM;
;                 float sq = 0.f;
; #pragma unroll
;                 for (int bj = 0; bj < 2; ++bj) { const int col = u.pn * 256 + bj * 128 + wc * 32 + 8 * fq;
;                     const f32x4 a0 = *(const f32x4*)(xi + col) + acc[ai][bj][m][0], a1 = *(const f32x4*)(xi + col + 4) + acc[ai][bj][m][1];
;                     *(f32x4*)(xout + (size_t)row * DM + col) = a0; *(f32x4*)(xout + (size_t)row * DM + col + 4) = a1;
;                     u32x4 w; w.x = pk(a0[0], a0[1]); w.y = pk(a0[2], a0[3]); w.z = pk(a1[0], a1[1]); w.w = pk(a1[2], a1[3]);
;                     *(u32x4*)(xb + (size_t)row * DM + col) = w;
;                     sq += dot4(a0) + dot4(a1); }
;                 sq += __shfl_xor(sq, 16); sq += __shfl_xor(sq, 32);
;                 if (fq == 0) atomicAdd(ssout + row, sq);
;             }
	v_pk_add_f32 v[22:23], v[22:23], v[138:139]
	v_pk_add_f32 v[24:25], v[24:25], v[140:141]
	v_pk_add_f32 v[18:19], v[18:19], v[144:145]
	v_pk_add_f32 v[20:21], v[20:21], v[146:147]
	global_store_dwordx4 v190, v[22:25], s[8:9] offset:512
	global_store_dwordx4 v191, v[18:21], s[8:9] offset:512
	v_cvt_pk_bf16_f32 v246, v22, v23
	v_cvt_pk_bf16_f32 v247, v24, v25
	v_cvt_pk_bf16_f32 v248, v18, v19
	v_cvt_pk_bf16_f32 v249, v20, v21
	v_fmac_f32_e32 v194, v22, v22
	v_fmac_f32_e32 v195, v18, v18
	v_fmac_f32_e32 v194, v23, v23
	v_fmac_f32_e32 v195, v19, v19
	v_fmac_f32_e32 v194, v24, v24
	v_fmac_f32_e32 v195, v20, v20
	v_fmac_f32_e32 v194, v25, v25
	v_fmac_f32_e32 v195, v21, v21
	global_store_dwordx2 v192, v[246:247], s[64:65] offset:256
	global_store_dwordx2 v193, v[248:249], s[64:65] offset:256
	s_nop 1
	v_add_f32_dpp v194, v194, v194 quad_perm:[1,0,3,2] row_mask:0xf bank_mask:0xf
	v_add_f32_dpp v195, v195, v195 quad_perm:[1,0,3,2] row_mask:0xf bank_mask:0xf
	s_nop 0
	v_add_f32_dpp v194, v194, v194 quad_perm:[2,3,0,1] row_mask:0xf bank_mask:0xf
	v_add_f32_dpp v195, v195, v195 quad_perm:[2,3,0,1] row_mask:0xf bank_mask:0xf
	s_nop 0
	v_add_f32_dpp v194, v194, v194 row_half_mirror row_mask:0xf bank_mask:0xf
	v_add_f32_dpp v195, v195, v195 row_half_mirror row_mask:0xf bank_mask:0xf
	s_nop 0
	s_mov_b32 exec_lo, 0x1010101
	s_mov_b32 exec_hi, 0x1010101
	global_atomic_add_f32 v182, v194, s[6:7] offset:640
	global_atomic_add_f32 v182, v195, s[6:7] offset:672
	s_mov_b64 exec, -1
	s_waitcnt vmcnt(20)
	v_add_u32_e32 v190, 0xb0000, v184
	v_add_u32_e32 v192, 0x58000, v183
	v_add_u32_e32 v191, 0x8000, v190
	v_add_u32_e32 v193, 0x4000, v192
	ds_write_b128 v186, v[14:17]
	ds_write_b128 v186, v[10:13] offset:16
	ds_read_b128 v[14:17], v187
	ds_read_b128 v[10:13], v187 offset:1152
	s_waitcnt lgkmcnt(0)
	v_pk_add_f32 v[14:15], v[14:15], v[148:149]
	v_pk_add_f32 v[16:17], v[16:17], v[150:151]
	v_pk_add_f32 v[10:11], v[10:11], v[152:153]
	v_pk_add_f32 v[12:13], v[12:13], v[154:155]
	global_store_dwordx4 v190, v[14:17], s[8:9]
	global_store_dwordx4 v191, v[10:13], s[8:9]
	v_cvt_pk_bf16_f32 v246, v14, v15
	v_cvt_pk_bf16_f32 v247, v16, v17
	v_cvt_pk_bf16_f32 v248, v10, v11
	v_cvt_pk_bf16_f32 v249, v12, v13
	v_mul_f32_e32 v194, v14, v14
	v_mul_f32_e32 v195, v10, v10
	v_fmac_f32_e32 v194, v15, v15
	v_fmac_f32_e32 v195, v11, v11
	v_fmac_f32_e32 v194, v16, v16
	v_fmac_f32_e32 v195, v12, v12
	v_fmac_f32_e32 v194, v17, v17
	v_fmac_f32_e32 v195, v13, v13
	global_store_dwordx2 v192, v[246:247], s[64:65]
	global_store_dwordx2 v193, v[248:249], s[64:65]
	ds_write_b128 v186, v[6:9]
	ds_write_b128 v186, v[2:5] offset:16
	ds_read_b128 v[6:9], v187
	ds_read_b128 v[2:5], v187 offset:1152
	s_waitcnt lgkmcnt(0)
	v_pk_add_f32 v[6:7], v[6:7], v[156:157]
	v_pk_add_f32 v[8:9], v[8:9], v[158:159]
	v_pk_add_f32 v[2:3], v[2:3], v[160:161]
	v_pk_add_f32 v[4:5], v[4:5], v[162:163]
	global_store_dwordx4 v190, v[6:9], s[8:9] offset:512
	global_store_dwordx4 v191, v[2:5], s[8:9] offset:512
	v_cvt_pk_bf16_f32 v246, v6, v7
	v_cvt_pk_bf16_f32 v247, v8, v9
	v_cvt_pk_bf16_f32 v248, v2, v3
	v_cvt_pk_bf16_f32 v249, v4, v5
	v_fmac_f32_e32 v194, v6, v6
	v_fmac_f32_e32 v195, v2, v2
	v_fmac_f32_e32 v194, v7, v7
	v_fmac_f32_e32 v195, v3, v3
	v_fmac_f32_e32 v194, v8, v8
	v_fmac_f32_e32 v195, v4, v4
	v_fmac_f32_e32 v194, v9, v9
	v_fmac_f32_e32 v195, v5, v5
	global_store_dwordx2 v192, v[246:247], s[64:65] offset:256
	global_store_dwordx2 v193, v[248:249], s[64:65] offset:256
	s_nop 1
	v_add_f32_dpp v194, v194, v194 quad_perm:[1,0,3,2] row_mask:0xf bank_mask:0xf
	v_add_f32_dpp v195, v195, v195 quad_perm:[1,0,3,2] row_mask:0xf bank_mask:0xf
	s_nop 0
	v_add_f32_dpp v194, v194, v194 quad_perm:[2,3,0,1] row_mask:0xf bank_mask:0xf
	v_add_f32_dpp v195, v195, v195 quad_perm:[2,3,0,1] row_mask:0xf bank_mask:0xf
	s_nop 0
	v_add_f32_dpp v194, v194, v194 row_half_mirror row_mask:0xf bank_mask:0xf
	v_add_f32_dpp v195, v195, v195 row_half_mirror row_mask:0xf bank_mask:0xf
	s_nop 0
	s_mov_b32 exec_lo, 0x1010101
	s_mov_b32 exec_hi, 0x1010101
	global_atomic_add_f32 v182, v194, s[6:7] offset:704
	global_atomic_add_f32 v182, v195, s[6:7] offset:736
	s_mov_b64 exec, -1
	s_waitcnt vmcnt(0)
	s_barrier
